# phase 0 weight transposes: flat loads/stores made global and LDS-pass entry waits counted (vmcnt 8/12) so the next unit's loads stay in flight during the current unit's LDS pass
# baseline (speedup 1.0000x reference)
.LBB0_74:
	v_ashrrev_i32_e32 v65, 3, v32
	v_lshlrev_b32_e32 v0, 2, v32
	v_add_u32_e32 v76, 64, v65
	v_add_u32_e32 v77, 0x80, v65
	v_add_u32_e32 v78, 0xc0, v65
	v_add_u32_e32 v79, 0x100, v65
	v_add_u32_e32 v80, 0x140, v65
	v_add_u32_e32 v81, 0x180, v65
	v_add_u32_e32 v82, 0x1c0, v65
	v_and_b32_e32 v64, 28, v0
	v_add_u32_e32 v0, s4, v65
	v_add_u32_e32 v2, s4, v76
	v_add_u32_e32 v8, s4, v77
	v_add_u32_e32 v10, s4, v78
	v_add_u32_e32 v16, s4, v79
	v_add_u32_e32 v18, s4, v80
	v_add_u32_e32 v24, s4, v81
	v_add_u32_e32 v26, s4, v82
	v_mad_i64_i32 v[0:1], s[2:3], s10, v0, 0
	v_mad_i64_i32 v[2:3], s[2:3], s10, v2, 0
	v_mad_i64_i32 v[8:9], s[2:3], s10, v8, 0
	v_mad_i64_i32 v[10:11], s[2:3], s10, v10, 0
	v_mad_i64_i32 v[16:17], s[2:3], s10, v16, 0
	v_mad_i64_i32 v[18:19], s[2:3], s10, v18, 0
	v_mad_i64_i32 v[24:25], s[2:3], s10, v24, 0
	v_mad_i64_i32 v[26:27], s[2:3], s10, v26, 0
	v_mov_b32_e32 v67, 0
	v_lshl_add_u64 v[0:1], v[0:1], 2, s[6:7]
	v_lshlrev_b32_e32 v66, 2, v64
	v_lshl_add_u64 v[2:3], v[2:3], 2, s[6:7]
	v_lshl_add_u64 v[8:9], v[8:9], 2, s[6:7]
	v_lshl_add_u64 v[10:11], v[10:11], 2, s[6:7]
	v_lshl_add_u64 v[16:17], v[16:17], 2, s[6:7]
	v_lshl_add_u64 v[18:19], v[18:19], 2, s[6:7]
	v_lshl_add_u64 v[24:25], v[24:25], 2, s[6:7]
	v_lshl_add_u64 v[26:27], v[26:27], 2, s[6:7]
	v_lshl_add_u64 v[0:1], v[0:1], 0, v[66:67]
	v_lshl_add_u64 v[4:5], v[2:3], 0, v[66:67]
	v_lshl_add_u64 v[8:9], v[8:9], 0, v[66:67]
	v_lshl_add_u64 v[12:13], v[10:11], 0, v[66:67]
	v_lshl_add_u64 v[16:17], v[16:17], 0, v[66:67]
	v_lshl_add_u64 v[20:21], v[18:19], 0, v[66:67]
	v_lshl_add_u64 v[24:25], v[24:25], 0, v[66:67]
	v_lshl_add_u64 v[28:29], v[26:27], 0, v[66:67]
	global_load_dwordx4 v[0:3], v[0:1], off
	s_nop 0
	global_load_dwordx4 v[4:7], v[4:5], off
	s_nop 0
	global_load_dwordx4 v[8:11], v[8:9], off
	s_nop 0
	global_load_dwordx4 v[12:15], v[12:13], off
	s_nop 0
	global_load_dwordx4 v[16:19], v[16:17], off
	s_nop 0
	global_load_dwordx4 v[20:23], v[20:21], off
	s_nop 0
	global_load_dwordx4 v[24:27], v[24:25], off
	s_nop 0
	global_load_dwordx4 v[28:31], v[28:29], off
	v_and_b32_e32 v33, 7, v32
	v_lshlrev_b32_e32 v34, 3, v33
	v_and_b32_e32 v35, 7, v65
	s_movk_i32 s2, 0x1040
	v_bitop3_b32 v37, v65, v34, -8 bitop3:0x6c
	v_mad_u32_u24 v33, v33, s2, 0
	v_and_b32_e32 v36, -8, v65
	v_or_b32_e32 v37, v37, v35
	v_lshl_add_u32 v83, v37, 1, v33
	v_add_u32_e32 v37, 64, v36
	v_xor_b32_e32 v37, v37, v34
	v_or_b32_e32 v37, v37, v35
	v_lshl_add_u32 v84, v37, 1, v33
	v_add_u32_e32 v37, 0x80, v36
	v_xor_b32_e32 v37, v37, v34
	v_or_b32_e32 v37, v37, v35
	v_lshl_add_u32 v85, v37, 1, v33
	v_add_u32_e32 v37, 0xc0, v36
	v_xor_b32_e32 v37, v37, v34
	v_or_b32_e32 v37, v37, v35
	v_lshl_add_u32 v86, v37, 1, v33
	v_add_u32_e32 v37, 0x100, v36
	v_xor_b32_e32 v37, v37, v34
	v_or_b32_e32 v37, v37, v35
	v_lshl_add_u32 v87, v37, 1, v33
	v_add_u32_e32 v37, 0x140, v36
	v_xor_b32_e32 v37, v37, v34
	v_or_b32_e32 v37, v37, v35
	v_lshl_add_u32 v88, v37, 1, v33
	v_add_u32_e32 v37, 0x180, v36
	v_add_u32_e32 v36, 0x1c0, v36
	v_xor_b32_e32 v37, v37, v34
	v_xor_b32_e32 v34, v36, v34
	v_or_b32_e32 v37, v37, v35
	v_or_b32_e32 v34, v34, v35
	v_ashrrev_i32_e32 v35, 8, v32
	v_ashrrev_i32_e32 v36, 6, v32
	v_bitop3_b32 v35, v35, v32, 63 bitop3:0x78
	v_lshl_add_u32 v89, v37, 1, v33
	v_lshl_add_u32 v90, v34, 1, v33
	v_and_b32_e32 v33, 63, v32
	s_movk_i32 s2, 0x410
	v_lshlrev_b32_e32 v38, 4, v35
	v_ashrrev_i32_e32 v37, 31, v36
	v_add_u32_e32 v35, 0x200, v32
	v_lshlrev_b32_e32 v34, 3, v33
	v_mul_lo_u32 v33, v36, s2
	v_lshlrev_b64 v[68:69], 13, v[36:37]
	v_ashrrev_i32_e32 v36, 6, v35
	v_ashrrev_i32_e32 v35, 8, v35
	v_mul_lo_u32 v37, v36, s2
	v_bitop3_b32 v35, v35, v32, 63 bitop3:0x78
	v_add_u32_e32 v39, 0, v37
	v_lshlrev_b32_e32 v40, 4, v35
	v_ashrrev_i32_e32 v37, 31, v36
	v_add_u32_e32 v35, 0x400, v32
	v_lshlrev_b64 v[70:71], 13, v[36:37]
	v_ashrrev_i32_e32 v36, 6, v35
	v_ashrrev_i32_e32 v35, 8, v35
	v_bitop3_b32 v35, v35, v32, 63 bitop3:0x78
	v_lshlrev_b32_e32 v42, 4, v35
	v_add_u32_e32 v35, 0x600, v32
	v_mul_lo_u32 v37, v36, s2
	v_lshlrev_b32_e32 v66, 1, v34
	v_ashrrev_i32_e32 v34, 6, v35
	v_ashrrev_i32_e32 v35, 8, v35
	v_add_u32_e32 v41, 0, v37
	v_ashrrev_i32_e32 v37, 31, v36
	v_bitop3_b32 v32, v35, v32, 63 bitop3:0x78
	v_mul_lo_u32 v35, v34, s2
	s_lshl_b32 s2, s86, 2
	v_add_u32_e32 v33, 0, v33
	v_lshlrev_b64 v[72:73], 13, v[36:37]
	v_add_u32_e32 v36, 0, v35
	v_lshlrev_b32_e32 v32, 4, v32
	v_ashrrev_i32_e32 v35, 31, v34
	s_add_i32 s68, s2, 0xffffafc0
	s_lshl_b32 s2, s86, 5
	s_mov_b32 s3, 0
	v_lshlrev_b64 v[74:75], 13, v[34:35]
	s_lshl_b32 s33, s84, 1
	s_lshl_b32 s87, s84, 3
	s_lshl_b32 s88, s84, 6
	s_add_i32 s69, s2, 0xfffd7e00
	s_lshl_b32 s89, s84, 2
	s_lshl_b32 s92, s84, 5
	v_add_u32_e32 v91, v33, v38
	v_add_u32_e32 v92, v39, v40
	v_add_u32_e32 v93, v41, v42
	v_add_u32_e32 v94, v36, v32
	s_mov_b64 s[6:7], s[0:1]
	s_mov_b32 s8, s4
	s_mov_b32 s71, s86
	s_branch .LBB0_79

.LBB0_76:
	v_add_u32_e32 v0, s4, v65
	v_add_u32_e32 v2, s4, v76
	v_add_u32_e32 v8, s4, v77
	v_add_u32_e32 v10, s4, v78
	v_add_u32_e32 v16, s4, v79
	v_add_u32_e32 v18, s4, v80
	v_add_u32_e32 v26, s4, v81
	v_add_u32_e32 v28, s4, v82
	v_mad_i64_i32 v[0:1], s[10:11], s20, v0, 0
	v_mad_i64_i32 v[2:3], s[10:11], s20, v2, 0
	v_mad_i64_i32 v[8:9], s[10:11], s20, v8, 0
	v_mad_i64_i32 v[10:11], s[10:11], s20, v10, 0
	v_mad_i64_i32 v[16:17], s[10:11], s20, v16, 0
	v_mad_i64_i32 v[18:19], s[10:11], s20, v18, 0
	v_mad_i64_i32 v[26:27], s[10:11], s20, v26, 0
	v_mad_i64_i32 v[28:29], s[10:11], s20, v28, 0
	v_lshl_add_u64 v[0:1], v[0:1], 2, s[14:15]
	v_lshlrev_b32_e32 v24, 2, v64
	v_mov_b32_e32 v25, v67
	v_lshl_add_u64 v[2:3], v[2:3], 2, s[14:15]
	v_lshl_add_u64 v[8:9], v[8:9], 2, s[14:15]
	v_lshl_add_u64 v[10:11], v[10:11], 2, s[14:15]
	v_lshl_add_u64 v[16:17], v[16:17], 2, s[14:15]
	v_lshl_add_u64 v[18:19], v[18:19], 2, s[14:15]
	v_lshl_add_u64 v[26:27], v[26:27], 2, s[14:15]
	v_lshl_add_u64 v[28:29], v[28:29], 2, s[14:15]
	v_lshl_add_u64 v[0:1], v[0:1], 0, v[24:25]
	v_lshl_add_u64 v[4:5], v[2:3], 0, v[24:25]
	v_lshl_add_u64 v[8:9], v[8:9], 0, v[24:25]
	v_lshl_add_u64 v[12:13], v[10:11], 0, v[24:25]
	v_lshl_add_u64 v[16:17], v[16:17], 0, v[24:25]
	v_lshl_add_u64 v[20:21], v[18:19], 0, v[24:25]
	v_lshl_add_u64 v[26:27], v[26:27], 0, v[24:25]
	v_lshl_add_u64 v[28:29], v[28:29], 0, v[24:25]
	global_load_dwordx4 v[0:3], v[0:1], off
	s_nop 0
	global_load_dwordx4 v[4:7], v[4:5], off
	s_nop 0
	global_load_dwordx4 v[8:11], v[8:9], off
	s_nop 0
	global_load_dwordx4 v[12:15], v[12:13], off
	s_nop 0
	global_load_dwordx4 v[16:19], v[16:17], off
	s_nop 0
	global_load_dwordx4 v[20:23], v[20:21], off
	s_nop 0
	global_load_dwordx4 v[24:27], v[26:27], off
	s_nop 0
	global_load_dwordx4 v[28:31], v[28:29], off
	s_waitcnt vmcnt(12)
	s_branch .LBB0_77

.LBB0_77:
	v_cvt_pk_bf16_f32 v95, v36, v67
	ds_write_b16 v83, v95
	v_cvt_pk_bf16_f32 v95, v37, v67
	ds_write_b16 v83, v95 offset:1040
	v_cvt_pk_bf16_f32 v95, v38, v67
	ds_write_b16 v83, v95 offset:2080
	v_cvt_pk_bf16_f32 v95, v39, v67
	ds_write_b16 v83, v95 offset:3120
	v_cvt_pk_bf16_f32 v95, v32, v67
	ds_write_b16 v84, v95
	v_cvt_pk_bf16_f32 v95, v33, v67
	ds_write_b16 v84, v95 offset:1040
	v_cvt_pk_bf16_f32 v95, v34, v67
	ds_write_b16 v84, v95 offset:2080
	v_cvt_pk_bf16_f32 v95, v35, v67
	ds_write_b16 v84, v95 offset:3120
	v_cvt_pk_bf16_f32 v95, v44, v67
	ds_write_b16 v85, v95
	v_cvt_pk_bf16_f32 v95, v45, v67
	ds_write_b16 v85, v95 offset:1040
	v_cvt_pk_bf16_f32 v95, v46, v67
	ds_write_b16 v85, v95 offset:2080
	v_cvt_pk_bf16_f32 v95, v47, v67
	ds_write_b16 v85, v95 offset:3120
	v_cvt_pk_bf16_f32 v95, v40, v67
	ds_write_b16 v86, v95
	v_cvt_pk_bf16_f32 v95, v41, v67
	ds_write_b16 v86, v95 offset:1040
	v_cvt_pk_bf16_f32 v95, v42, v67
	ds_write_b16 v86, v95 offset:2080
	v_cvt_pk_bf16_f32 v95, v43, v67
	ds_write_b16 v86, v95 offset:3120
	v_cvt_pk_bf16_f32 v95, v52, v67
	ds_write_b16 v87, v95
	v_cvt_pk_bf16_f32 v95, v53, v67
	ds_write_b16 v87, v95 offset:1040
	v_cvt_pk_bf16_f32 v95, v54, v67
	ds_write_b16 v87, v95 offset:2080
	v_cvt_pk_bf16_f32 v95, v55, v67
	ds_write_b16 v87, v95 offset:3120
	v_cvt_pk_bf16_f32 v95, v48, v67
	ds_write_b16 v88, v95
	v_cvt_pk_bf16_f32 v95, v49, v67
	ds_write_b16 v88, v95 offset:1040
	v_cvt_pk_bf16_f32 v95, v50, v67
	ds_write_b16 v88, v95 offset:2080
	v_cvt_pk_bf16_f32 v95, v51, v67
	ds_write_b16 v88, v95 offset:3120
	v_cvt_pk_bf16_f32 v95, v60, v67
	ds_write_b16 v89, v95
	v_cvt_pk_bf16_f32 v95, v61, v67
	ds_write_b16 v89, v95 offset:1040
	v_cvt_pk_bf16_f32 v95, v62, v67
	ds_write_b16 v89, v95 offset:2080
	v_cvt_pk_bf16_f32 v95, v63, v67
	ds_write_b16 v89, v95 offset:3120
	v_cvt_pk_bf16_f32 v95, v56, v67
	ds_write_b16 v90, v95
	v_cvt_pk_bf16_f32 v95, v57, v67
	ds_write_b16 v90, v95 offset:1040
	v_cvt_pk_bf16_f32 v95, v58, v67
	s_ashr_i32 s9, s8, 31
	s_add_i32 s71, s70, s84
	ds_write_b16 v90, v95 offset:2080
	v_cvt_pk_bf16_f32 v95, v59, v67
	ds_write_b16 v90, v95 offset:3120
	s_waitcnt lgkmcnt(0)
	s_barrier
	s_lshl_b64 s[10:11], s[8:9], 1
	ds_read_b128 v[96:99], v91
	s_add_u32 s10, s6, s10
	s_addc_u32 s11, s7, s11
	v_lshl_add_u64 v[100:101], s[10:11], 0, v[66:67]
	v_lshl_add_u64 v[102:103], v[100:101], 0, v[68:69]
	s_waitcnt lgkmcnt(0)
	global_store_dwordx4 v[102:103], v[96:99], off
	ds_read_b128 v[96:99], v92
	v_lshl_add_u64 v[102:103], v[100:101], 0, v[70:71]
	s_add_i32 s68, s68, s87
	s_add_i32 s69, s69, s88
	s_cmpk_gt_i32 s71, 0x1c0f
	s_waitcnt lgkmcnt(0)
	global_store_dwordx4 v[102:103], v[96:99], off
	ds_read_b128 v[96:99], v93
	v_lshl_add_u64 v[102:103], v[100:101], 0, v[72:73]
	v_lshl_add_u64 v[100:101], v[100:101], 0, v[74:75]
	s_cselect_b64 s[10:11], -1, 0
	s_waitcnt lgkmcnt(0)
	global_store_dwordx4 v[102:103], v[96:99], off
	ds_read_b128 v[96:99], v94
	s_waitcnt lgkmcnt(0)
	global_store_dwordx4 v[100:101], v[96:99], off
	s_waitcnt lgkmcnt(0)
	s_barrier

.LBB0_92:
	v_add_u32_e32 v32, s8, v65
	v_add_u32_e32 v34, s8, v76
	v_add_u32_e32 v40, s8, v77
	v_add_u32_e32 v42, s8, v78
	v_add_u32_e32 v48, s8, v79
	v_add_u32_e32 v50, s8, v80
	v_add_u32_e32 v58, s8, v81
	v_add_u32_e32 v60, s8, v82
	v_mad_i64_i32 v[32:33], s[12:13], s24, v32, 0
	v_mad_i64_i32 v[34:35], s[12:13], s24, v34, 0
	v_mad_i64_i32 v[40:41], s[12:13], s24, v40, 0
	v_mad_i64_i32 v[42:43], s[12:13], s24, v42, 0
	v_mad_i64_i32 v[48:49], s[12:13], s24, v48, 0
	v_mad_i64_i32 v[50:51], s[12:13], s24, v50, 0
	v_mad_i64_i32 v[58:59], s[12:13], s24, v58, 0
	v_mad_i64_i32 v[60:61], s[12:13], s24, v60, 0
	v_lshl_add_u64 v[32:33], v[32:33], 2, s[16:17]
	v_lshlrev_b32_e32 v56, 2, v64
	v_mov_b32_e32 v57, v67
	v_lshl_add_u64 v[34:35], v[34:35], 2, s[16:17]
	v_lshl_add_u64 v[40:41], v[40:41], 2, s[16:17]
	v_lshl_add_u64 v[42:43], v[42:43], 2, s[16:17]
	v_lshl_add_u64 v[48:49], v[48:49], 2, s[16:17]
	v_lshl_add_u64 v[50:51], v[50:51], 2, s[16:17]
	v_lshl_add_u64 v[58:59], v[58:59], 2, s[16:17]
	v_lshl_add_u64 v[60:61], v[60:61], 2, s[16:17]
	v_lshl_add_u64 v[32:33], v[32:33], 0, v[56:57]
	v_lshl_add_u64 v[34:35], v[34:35], 0, v[56:57]
	v_lshl_add_u64 v[40:41], v[40:41], 0, v[56:57]
	v_lshl_add_u64 v[42:43], v[42:43], 0, v[56:57]
	v_lshl_add_u64 v[48:49], v[48:49], 0, v[56:57]
	v_lshl_add_u64 v[50:51], v[50:51], 0, v[56:57]
	v_lshl_add_u64 v[58:59], v[58:59], 0, v[56:57]
	v_lshl_add_u64 v[56:57], v[60:61], 0, v[56:57]
	global_load_dwordx4 v[36:39], v[32:33], off
	s_nop 0
	global_load_dwordx4 v[32:35], v[34:35], off
	s_nop 0
	global_load_dwordx4 v[44:47], v[40:41], off
	s_nop 0
	global_load_dwordx4 v[40:43], v[42:43], off
	s_nop 0
	global_load_dwordx4 v[52:55], v[48:49], off
	s_nop 0
	global_load_dwordx4 v[48:51], v[50:51], off
	s_nop 0
	global_load_dwordx4 v[60:63], v[58:59], off
	s_nop 0
	global_load_dwordx4 v[56:59], v[56:57], off
	s_waitcnt vmcnt(8) lgkmcnt(0)
	s_branch .Lp0t_passa

.Lp0t_passa:
	v_cvt_pk_bf16_f32 v95, v0, v67
	ds_write_b16 v83, v95
	v_cvt_pk_bf16_f32 v95, v1, v67
	ds_write_b16 v83, v95 offset:1040
	v_cvt_pk_bf16_f32 v95, v2, v67
	ds_write_b16 v83, v95 offset:2080
	v_cvt_pk_bf16_f32 v95, v3, v67
	ds_write_b16 v83, v95 offset:3120
	v_cvt_pk_bf16_f32 v95, v4, v67
	ds_write_b16 v84, v95
	v_cvt_pk_bf16_f32 v95, v5, v67
	ds_write_b16 v84, v95 offset:1040
	v_cvt_pk_bf16_f32 v95, v6, v67
	ds_write_b16 v84, v95 offset:2080
	v_cvt_pk_bf16_f32 v95, v7, v67
	ds_write_b16 v84, v95 offset:3120
	v_cvt_pk_bf16_f32 v95, v8, v67
	ds_write_b16 v85, v95
	v_cvt_pk_bf16_f32 v95, v9, v67
	ds_write_b16 v85, v95 offset:1040
	v_cvt_pk_bf16_f32 v95, v10, v67
	ds_write_b16 v85, v95 offset:2080
	v_cvt_pk_bf16_f32 v95, v11, v67
	ds_write_b16 v85, v95 offset:3120
	v_cvt_pk_bf16_f32 v95, v12, v67
	ds_write_b16 v86, v95
	v_cvt_pk_bf16_f32 v95, v13, v67
	ds_write_b16 v86, v95 offset:1040
	v_cvt_pk_bf16_f32 v95, v14, v67
	ds_write_b16 v86, v95 offset:2080
	v_cvt_pk_bf16_f32 v95, v15, v67
	ds_write_b16 v86, v95 offset:3120
	v_cvt_pk_bf16_f32 v95, v16, v67
	ds_write_b16 v87, v95
	v_cvt_pk_bf16_f32 v95, v17, v67
	ds_write_b16 v87, v95 offset:1040
	v_cvt_pk_bf16_f32 v95, v18, v67
	ds_write_b16 v87, v95 offset:2080
	v_cvt_pk_bf16_f32 v95, v19, v67
	ds_write_b16 v87, v95 offset:3120
	v_cvt_pk_bf16_f32 v95, v20, v67
	ds_write_b16 v88, v95
	v_cvt_pk_bf16_f32 v95, v21, v67
	ds_write_b16 v88, v95 offset:1040
	v_cvt_pk_bf16_f32 v95, v22, v67
	ds_write_b16 v88, v95 offset:2080
	v_cvt_pk_bf16_f32 v95, v23, v67
	ds_write_b16 v88, v95 offset:3120
	v_cvt_pk_bf16_f32 v95, v24, v67
	ds_write_b16 v89, v95
	v_cvt_pk_bf16_f32 v95, v25, v67
	ds_write_b16 v89, v95 offset:1040
	v_cvt_pk_bf16_f32 v95, v26, v67
	ds_write_b16 v89, v95 offset:2080
	v_cvt_pk_bf16_f32 v95, v27, v67
	ds_write_b16 v89, v95 offset:3120
	v_cvt_pk_bf16_f32 v95, v28, v67
	ds_write_b16 v90, v95
	v_cvt_pk_bf16_f32 v95, v29, v67
	ds_write_b16 v90, v95 offset:1040
	v_cvt_pk_bf16_f32 v95, v30, v67
	s_ashr_i32 s5, s4, 31
	ds_write_b16 v90, v95 offset:2080
	v_cvt_pk_bf16_f32 v95, v31, v67
	ds_write_b16 v90, v95 offset:3120
	s_waitcnt lgkmcnt(0)
	s_barrier
	s_lshl_b64 s[12:13], s[4:5], 1
	ds_read_b128 v[96:99], v91
	s_add_u32 s12, s0, s12
	s_addc_u32 s13, s1, s13
	v_lshl_add_u64 v[100:101], s[12:13], 0, v[66:67]
	v_lshl_add_u64 v[102:103], v[100:101], 0, v[68:69]
	s_waitcnt lgkmcnt(0)
	global_store_dwordx4 v[102:103], v[96:99], off
	ds_read_b128 v[96:99], v92
	v_lshl_add_u64 v[102:103], v[100:101], 0, v[70:71]
	s_andn2_b64 vcc, exec, s[10:11]
	s_mov_b64 s[10:11], -1
	s_waitcnt lgkmcnt(0)
	global_store_dwordx4 v[102:103], v[96:99], off
	ds_read_b128 v[96:99], v93
	v_lshl_add_u64 v[102:103], v[100:101], 0, v[72:73]
	v_lshl_add_u64 v[100:101], v[100:101], 0, v[74:75]
	s_waitcnt lgkmcnt(0)
	global_store_dwordx4 v[102:103], v[96:99], off
	ds_read_b128 v[96:99], v94
	s_waitcnt lgkmcnt(0)
	global_store_dwordx4 v[100:101], v[96:99], off
	s_waitcnt lgkmcnt(0)
	s_barrier
	s_cbranch_vccnz .LBB0_78
	s_add_i32 s5, s33, s71
	s_cmpk_gt_i32 s5, 0x1c0f
	s_cbranch_scc1 .Lp0t_77w
	v_readlane_b32 s52, v254, 44
	v_readlane_b32 s53, v254, 45
	v_readlane_b32 s54, v254, 46
	v_readlane_b32 s55, v254, 47
	v_readlane_b32 s56, v254, 48
	v_readlane_b32 s57, v254, 49
	v_readlane_b32 s58, v254, 50
	v_readlane_b32 s59, v254, 51
	v_readlane_b32 s60, v254, 52
	v_readlane_b32 s61, v254, 53
	v_readlane_b32 s62, v254, 54
	v_readlane_b32 s63, v254, 55
	v_readlane_b32 s64, v254, 56
	v_readlane_b32 s65, v254, 57
	v_readlane_b32 s66, v254, 58
	v_readlane_b32 s67, v254, 59
	s_mov_b64 s[10:11], s[62:63]
	v_readlane_b32 s52, v254, 60
	v_readlane_b32 s53, v254, 61
	v_readlane_b32 s54, v254, 62
	v_readlane_b32 s55, v254, 63
	v_readlane_b32 s56, v253, 0
	v_readlane_b32 s57, v253, 1
	v_readlane_b32 s58, v253, 2
	v_readlane_b32 s59, v253, 3
	v_readlane_b32 s60, v253, 4
	v_readlane_b32 s61, v253, 5
	v_readlane_b32 s62, v253, 6
	v_readlane_b32 s63, v253, 7
	v_readlane_b32 s64, v253, 8
	v_readlane_b32 s65, v253, 9
	v_readlane_b32 s66, v253, 10
	v_readlane_b32 s67, v253, 11
	s_mov_b64 s[20:21], s[58:59]
	s_mov_b64 s[12:13], s[64:65]
	s_mov_b64 s[16:17], s[66:67]
	v_readlane_b32 s52, v254, 12
	v_readlane_b32 s53, v254, 13
	s_mov_b64 s[34:35], s[52:53]
	s_cmpk_gt_i32 s5, 0x140f
	s_mov_b64 s[24:25], -1
	v_readlane_b32 s54, v254, 14
	v_readlane_b32 s55, v254, 15
	v_readlane_b32 s56, v254, 16
	v_readlane_b32 s57, v254, 17
	v_readlane_b32 s58, v254, 18
	v_readlane_b32 s59, v254, 19
	v_readlane_b32 s60, v254, 20
	v_readlane_b32 s61, v254, 21
	v_readlane_b32 s62, v254, 22
	v_readlane_b32 s63, v254, 23
	v_readlane_b32 s64, v254, 24
	v_readlane_b32 s65, v254, 25
	v_readlane_b32 s66, v254, 26
	v_readlane_b32 s67, v254, 27
	s_cbranch_scc0 .LBB0_97
	s_add_i32 s0, s5, 0xffffebf0
	s_lshr_b32 s2, s0, 10
	s_add_i32 s0, s88, s69
	s_and_b32 s4, s0, 0xfe0
	s_lshl_b64 s[0:1], s[2:3], 25
	s_add_u32 s0, s34, s0
	s_addc_u32 s1, s35, s1
	s_lshl_b32 s9, s4, 13
	s_add_u32 s0, s0, s9
	s_addc_u32 s1, s1, 0
	s_lshl_b64 s[14:15], s[2:3], 26
	s_add_u32 s2, s20, s14
	s_addc_u32 s9, s21, s15
	s_lshl_b32 s4, s4, 2
	s_add_u32 s14, s2, s4
	s_addc_u32 s15, s9, 0
	s_add_i32 s2, s87, s68
	s_and_b32 s4, s2, 0xe00
	s_mov_b64 s[24:25], 0
